# v32: v31 + softmax row sums accumulated with v_pk_add_f32 (32 packed adds per tile instead of 64 scalar adds), f32 throughout
# speedup vs baseline: 1.0060x; 1.0007x over previous
.LBB0_747:
	s_and_b64 vcc, exec, s[10:11]
	s_cbranch_vccz .LBB0_751
	v_mov_b32_e32 v10, v232
	s_load_dwordx8 s[52:59], s[44:45], 0x60
	v_and_b32_e32 v181, 63, v10
	v_readlane_b32 s10, v255, 20
	v_mov_b32_e32 v3, v0
	s_load_dwordx2 s[42:43], s[44:45], 0xb0
	v_or_b32_e32 v2, s10, v181
	v_lshlrev_b64 v[2:3], 2, v[2:3]
	s_waitcnt lgkmcnt(0)
	v_lshl_add_u64 v[4:5], s[52:53], 0, v[2:3]
	global_load_dword v11, v[4:5], off
	v_lshl_add_u64 v[4:5], s[54:55], 0, v[2:3]
	global_load_dword v12, v[4:5], off
	v_lshl_add_u64 v[4:5], s[56:57], 0, v[2:3]
	v_lshl_add_u64 v[2:3], s[58:59], 0, v[2:3]
	global_load_dword v13, v[4:5], off
	global_load_dword v14, v[2:3], off
	s_add_i32 s6, s37, s48
	s_lshl_b32 s14, s36, 7
	s_lshl_b32 s30, s36, 8
	v_readlane_b32 s11, v255, 21
	s_add_u32 s10, s42, s47
	s_addc_u32 s11, s43, s46
	s_add_u32 s36, s10, s30
	s_addc_u32 s37, s11, 0
	s_lshl_b32 s10, s27, 10
	s_or_b32 s10, s14, s10
	s_mul_hi_i32 s11, s10, 0x2200
	s_mulk_i32 s10, 0x2200
	v_ashrrev_i32_e32 v50, 4, v10
	s_add_u32 s10, s42, s10
	v_ashrrev_i32_e32 v51, 31, v50
	v_and_b32_e32 v177, 15, v10
	s_addc_u32 s11, s43, s11
	v_lshlrev_b64 v[52:53], 11, v[50:51]
	s_add_u32 s40, s10, 0xe010000
	v_lshl_add_u64 v[2:3], s[36:37], 0, v[52:53]
	v_lshlrev_b32_e32 v124, 4, v177
	v_mov_b32_e32 v125, v0
	s_addc_u32 s41, s11, 0
	v_lshl_add_u64 v[2:3], v[2:3], 0, v[124:125]
	s_mov_b32 s15, 0x16810000
	v_mov_b64_e32 v[4:5], s[40:41]
	s_movk_i32 s35, 0x2200
	v_add_co_u32_e32 v6, vcc, s15, v2
	v_mad_i64_i32 v[4:5], s[36:37], v50, s35, v[4:5]
	s_nop 0
	v_addc_co_u32_e32 v7, vcc, 0, v3, vcc
	s_mov_b32 s15, 0x16820000
	v_lshl_add_u64 v[4:5], v[4:5], 0, v[124:125]
	global_load_dwordx4 v[18:21], v[6:7], off
	global_load_dwordx4 v[22:25], v[4:5], off
	v_add_co_u32_e32 v6, vcc, s15, v2
	s_mov_b32 s15, 0x44000
	s_nop 0
	v_addc_co_u32_e32 v7, vcc, 0, v3, vcc
	v_add_co_u32_e32 v8, vcc, s15, v4
	s_mov_b32 s15, 0x16830000
	s_nop 0
	v_addc_co_u32_e32 v9, vcc, 0, v5, vcc
	global_load_dwordx4 v[26:29], v[6:7], off
	global_load_dwordx4 v[30:33], v[8:9], off
	v_add_co_u32_e32 v6, vcc, s15, v2
	s_mov_b32 s15, 0x88000
	s_nop 0
	v_addc_co_u32_e32 v7, vcc, 0, v3, vcc
	v_add_co_u32_e32 v8, vcc, s15, v4
	s_mov_b32 s15, 0x16840000
	s_nop 0
	v_addc_co_u32_e32 v9, vcc, 0, v5, vcc
	v_add_co_u32_e32 v2, vcc, s15, v2
	s_mov_b32 s15, 0xcc000
	s_nop 0
	v_addc_co_u32_e32 v3, vcc, 0, v3, vcc
	v_add_co_u32_e32 v4, vcc, s15, v4
	global_load_dwordx4 v[34:37], v[6:7], off
	global_load_dwordx4 v[38:41], v[8:9], off
	v_addc_co_u32_e32 v5, vcc, 0, v5, vcc
	global_load_dwordx4 v[42:45], v[2:3], off
	global_load_dwordx4 v[46:49], v[4:5], off
	v_ashrrev_i32_e32 v4, 2, v10
	v_and_b32_e32 v4, 0xffffffe0, v4
	v_add_u32_e32 v180, s6, v4
	v_ashrrev_i32_e32 v182, 6, v10
	v_and_b32_e32 v179, 1, v182
	v_mov_b32_e32 v55, v0
	v_lshlrev_b32_e32 v54, 7, v179
	s_waitcnt vmcnt(10)
	v_mul_f32_e32 v2, v11, v12
	ds_bpermute_b32 v2, v1, v2
	v_and_b32_e32 v56, 48, v10
	v_mov_b32_e32 v57, v0
	s_waitcnt vmcnt(8)
	v_mul_f32_e32 v3, v13, v14
	ds_bpermute_b32 v3, v1, v3
	s_waitcnt lgkmcnt(1)
	v_fmac_f32_e32 v2, v11, v12
	ds_bpermute_b32 v5, v176, v2
	s_mov_b32 s6, 0x14610000
	s_mov_b64 s[36:37], 0x14610000
	s_waitcnt lgkmcnt(1)
	v_fmac_f32_e32 v3, v13, v14
	ds_bpermute_b32 v6, v176, v3
	s_waitcnt lgkmcnt(1)
	v_add_f32_e32 v4, v2, v5
	v_or_b32_e32 v2, v180, v177
	v_bfe_u32 v178, v10, 4, 2
	v_lshlrev_b32_e32 v51, 2, v50
	s_waitcnt lgkmcnt(0)
	v_add_f32_e32 v5, v3, v6
	ds_bpermute_b32 v6, v175, v4
	ds_bpermute_b32 v7, v175, v5
	v_ashrrev_i32_e32 v3, 31, v2
	v_lshlrev_b64 v[2:3], 11, v[2:3]
	v_lshl_add_u64 v[2:3], s[42:43], 0, v[2:3]
	s_waitcnt lgkmcnt(1)
	v_add_f32_e32 v4, v4, v6
	s_waitcnt lgkmcnt(0)
	v_add_f32_e32 v5, v5, v7
	ds_bpermute_b32 v6, v174, v4
	ds_bpermute_b32 v7, v174, v5
	v_lshl_add_u64 v[2:3], v[2:3], 0, s[30:31]
	v_lshl_add_u64 v[2:3], v[2:3], 0, v[54:55]
	v_lshrrev_b32_e32 v55, 1, v50
	s_waitcnt lgkmcnt(1)
	v_add_f32_e32 v132, v4, v6
	s_waitcnt lgkmcnt(0)
	v_add_f32_e32 v133, v5, v7
	v_lshl_add_u64 v[6:7], v[2:3], 0, v[56:57]
	v_add_co_u32_e32 v4, vcc, s6, v6
	s_mov_b32 s6, 0x14618000
	s_nop 0
	v_addc_co_u32_e32 v5, vcc, 0, v7, vcc
	v_lshl_add_u64 v[2:3], v[6:7], 0, s[36:37]
	v_add_co_u32_e32 v6, vcc, s6, v6
	global_load_dwordx4 v[10:13], v[4:5], off
	s_nop 0
	global_load_dwordx4 v[2:5], v[2:3], off offset:64
	v_addc_co_u32_e32 v7, vcc, 0, v7, vcc
	global_load_dwordx4 v[14:17], v[6:7], off
	s_nop 0
	global_load_dwordx4 v[6:9], v[6:7], off offset:64
	v_and_b32_e32 v51, 16, v51
	v_and_b32_e32 v55, 12, v55
	v_and_b32_e32 v57, 0xfffffe3, v50
	v_or3_b32 v51, v57, v51, v55
	s_movk_i32 s6, 0x120
	v_mul_lo_u32 v55, v50, s6
	v_mad_u64_u32 v[126:127], s[36:37], v51, s6, v[124:125]
	s_mov_b32 s6, 0x12000
	v_add3_u32 v127, v55, v124, s6
	v_add_u32_e32 v51, 0, v126
	v_add_u32_e32 v55, 0, v127
	s_waitcnt vmcnt(11)
	ds_write_b128 v51, v[18:21]
	s_waitcnt vmcnt(10)
	ds_write_b128 v55, v[22:25]
	s_waitcnt vmcnt(9)
	ds_write_b128 v51, v[26:29] offset:9216
	s_waitcnt vmcnt(8)
	ds_write_b128 v55, v[30:33] offset:9216
	s_waitcnt vmcnt(7)
	ds_write_b128 v51, v[34:37] offset:18432
	s_waitcnt vmcnt(6)
	ds_write_b128 v55, v[38:41] offset:18432
	s_waitcnt vmcnt(5)
	ds_write_b128 v51, v[42:45] offset:27648
	s_waitcnt vmcnt(4)
	ds_write_b128 v55, v[46:49] offset:27648
	s_add_i32 s6, 0, 0x12000
	v_mul_u32_u24_e32 v19, 0x120, v177
	v_add3_u32 v183, s6, v56, v19
	s_lshl_b32 s6, s26, 3
	s_and_b32 s6, s6, 0x700
	ds_bpermute_b32 v134, v173, v132
	ds_bpermute_b32 v135, v173, v133
	s_add_u32 s6, s42, s6
	v_add_u32_e32 v18, 0, v54
	s_addc_u32 s18, s43, 0
	v_add3_u32 v137, v18, v56, v19
	s_add_u32 s26, s6, s47
	v_mov_b64_e32 v[18:19], s[10:11]
	s_addc_u32 s27, s18, s46
	v_mad_i64_i32 v[130:131], s[10:11], v50, s35, v[18:19]
	v_mov_b32_e32 v18, 0
	s_mov_b32 s15, 0
	v_lshl_add_u64 v[128:129], s[26:27], 0, v[52:53]
	v_mov_b32_e32 v19, v18
	v_mov_b32_e32 v20, v18
	v_mov_b32_e32 v21, v18
	v_mov_b32_e32 v22, v18
	v_mov_b32_e32 v23, v18
	v_mov_b32_e32 v24, v18
	v_mov_b32_e32 v25, v18
	v_mov_b32_e32 v26, v18
	v_mov_b32_e32 v27, v18
	v_mov_b32_e32 v28, v18
	v_mov_b32_e32 v29, v18
	v_mov_b32_e32 v30, v18
	v_mov_b32_e32 v31, v18
	v_mov_b32_e32 v32, v18
	v_mov_b32_e32 v33, v18
	v_mov_b32_e32 v38, v18
	v_mov_b32_e32 v39, v18
	v_mov_b32_e32 v40, v18
	v_mov_b32_e32 v41, v18
	v_mov_b32_e32 v46, v18
	v_mov_b32_e32 v47, v18
	v_mov_b32_e32 v48, v18
	v_mov_b32_e32 v49, v18
	v_mov_b32_e32 v62, v18
	v_mov_b32_e32 v63, v18
	v_mov_b32_e32 v64, v18
	v_mov_b32_e32 v65, v18
	v_mov_b32_e32 v74, v18
	v_mov_b32_e32 v75, v18
	v_mov_b32_e32 v76, v18
	v_mov_b32_e32 v77, v18
	v_mov_b32_e32 v34, v18
	v_mov_b32_e32 v35, v18
	v_mov_b32_e32 v36, v18
	v_mov_b32_e32 v37, v18
	v_mov_b32_e32 v42, v18
	v_mov_b32_e32 v43, v18
	v_mov_b32_e32 v44, v18
	v_mov_b32_e32 v45, v18
	v_mov_b32_e32 v50, v18
	v_mov_b32_e32 v51, v18
	v_mov_b32_e32 v52, v18
	v_mov_b32_e32 v53, v18
	v_mov_b32_e32 v54, v18
	v_mov_b32_e32 v55, v18
	v_mov_b32_e32 v56, v18
	v_mov_b32_e32 v57, v18
	v_mov_b32_e32 v58, v18
	v_mov_b32_e32 v59, v18
	v_mov_b32_e32 v60, v18
	v_mov_b32_e32 v61, v18
	v_mov_b32_e32 v66, v18
	v_mov_b32_e32 v67, v18
	v_mov_b32_e32 v68, v18
	v_mov_b32_e32 v69, v18
	v_mov_b32_e32 v70, v18
	v_mov_b32_e32 v71, v18
	v_mov_b32_e32 v72, v18
	v_mov_b32_e32 v73, v18
	v_mov_b32_e32 v78, v18
	v_mov_b32_e32 v79, v18
	v_mov_b32_e32 v80, v18
	v_mov_b32_e32 v81, v18
	v_mov_b32_e32 v122, v18
	v_mov_b32_e32 v123, v18
	s_mov_b32 s11, 0xe054000
	s_mov_b32 s18, 0x16870000
	s_mov_b32 s26, 0xe098000
	s_mov_b32 s27, 0x16880000
	s_mov_b32 s30, 0xe0dc000
	s_mov_b64 s[36:37], 0x40000
	s_waitcnt lgkmcnt(0)
	s_barrier
	s_waitcnt vmcnt(0) lgkmcnt(0)
	v_writelane_b32 v175, s64, 0
	v_writelane_b32 v175, s65, 1
	v_writelane_b32 v175, s66, 2
	v_writelane_b32 v175, s67, 3
	v_writelane_b32 v175, s68, 4
	v_writelane_b32 v175, s69, 5
	v_writelane_b32 v175, s70, 6
	v_writelane_b32 v175, s71, 7
	v_writelane_b32 v175, s72, 8
	v_writelane_b32 v175, s73, 9
	v_writelane_b32 v175, s74, 10
	v_writelane_b32 v175, s75, 11
	v_writelane_b32 v175, s76, 12
	v_writelane_b32 v175, s77, 13
	v_writelane_b32 v175, s78, 14
	v_writelane_b32 v175, s79, 15
	v_lshl_add_u64 v[138:139], v[128:129], 0, v[124:125]
	v_lshl_add_u64 v[140:141], v[130:131], 0, v[124:125]
	s_nop 1
	v_readfirstlane_b32 s64, v138
	v_readfirstlane_b32 s65, v139
	v_readfirstlane_b32 s72, v140
	v_readfirstlane_b32 s73, v141
	s_nop 3
	v_subrev_u32_e32 v124, s64, v138
	v_subrev_u32_e32 v125, s72, v140
	s_add_u32 s66, s64, s97
	s_addc_u32 s67, s65, 0
	s_add_u32 s68, s64, s18
	s_addc_u32 s69, s65, 0
	s_add_u32 s70, s64, s27
	s_addc_u32 s71, s65, 0
	s_add_u32 s64, s64, s96
	s_addc_u32 s65, s65, 0
	s_add_u32 s74, s72, s11
	s_addc_u32 s75, s73, 0
	s_add_u32 s74, s74, 0x100
	s_addc_u32 s75, s75, 0
	s_add_u32 s76, s72, s26
	s_addc_u32 s77, s73, 0
	s_add_u32 s76, s76, 0x100
	s_addc_u32 s77, s77, 0
	s_add_u32 s78, s72, s30
	s_addc_u32 s79, s73, 0
	s_add_u32 s78, s78, 0x100
	s_addc_u32 s79, s79, 0
	s_add_u32 s72, s72, s91
	s_addc_u32 s73, s73, 0
	s_add_u32 s72, s72, 0x100
	s_addc_u32 s73, s73, 0
	v_mov_b32_e32 v200, v123
	v_mov_b32_e32 v201, 0
	v_mov_b32_e32 v202, v122
	v_mov_b32_e32 v203, 0
	s_mov_b32 s15, 0
	s_nop 4
.Lattn_nf_loop:
	s_and_b32 s10, s15, 1
	s_mul_i32 s6, s10, 0x9000
	v_add_u32_e32 v136, s6, v137
	v_add_u32_e32 v170, s6, v183
	s_sub_u32 s10, 0x9000, s6
	ds_read_b128 v[98:101], v136 offset:0
	ds_read_b128 v[102:105], v136 offset:64
	ds_read_b128 v[106:109], v136 offset:4608
	ds_read_b128 v[110:113], v136 offset:4672
	v_add_u32_e32 v171, s10, v126
	v_add_u32_e32 v173, s10, v127
	global_load_dwordx4 v[82:85], v124, s[64:65]
	global_load_dwordx4 v[86:89], v124, s[66:67]
	global_load_dwordx4 v[90:93], v124, s[68:69]
	global_load_dwordx4 v[94:97], v124, s[70:71]
	v_add_u32_e32 v124, s36, v124
	s_waitcnt lgkmcnt(3)
	v_mfma_f32_16x16x32_bf16 v[138:141], v[98:101], v[10:13], 0
	v_mfma_f32_16x16x32_bf16 v[142:145], v[98:101], v[14:17], 0
	s_waitcnt lgkmcnt(2)
	v_mfma_f32_16x16x32_bf16 v[138:141], v[102:105], v[2:5], v[138:141]
	v_mfma_f32_16x16x32_bf16 v[142:145], v[102:105], v[6:9], v[142:145]
	ds_read_b128 v[98:101], v136 offset:9216
	ds_read_b128 v[102:105], v136 offset:9280
	s_waitcnt lgkmcnt(3)
	v_mfma_f32_16x16x32_bf16 v[146:149], v[106:109], v[10:13], 0
	v_mfma_f32_16x16x32_bf16 v[150:153], v[106:109], v[14:17], 0
	s_waitcnt lgkmcnt(2)
	v_mfma_f32_16x16x32_bf16 v[146:149], v[110:113], v[2:5], v[146:149]
	v_mfma_f32_16x16x32_bf16 v[150:153], v[110:113], v[6:9], v[150:153]
	ds_read_b128 v[106:109], v136 offset:13824
	ds_read_b128 v[110:113], v136 offset:13888
	v_exp_f32_e32 v138, v138
	v_exp_f32_e32 v139, v139
	v_exp_f32_e32 v140, v140
	v_exp_f32_e32 v141, v141
	v_exp_f32_e32 v142, v142
	v_exp_f32_e32 v143, v143
	v_exp_f32_e32 v144, v144
	v_exp_f32_e32 v145, v145
	v_pk_add_f32 v[200:201], v[138:139], v[200:201]
	v_pk_add_f32 v[202:203], v[142:143], v[202:203]
	v_pk_add_f32 v[200:201], v[140:141], v[200:201]
	v_pk_add_f32 v[202:203], v[144:145], v[202:203]
	s_waitcnt lgkmcnt(3)
	v_mfma_f32_16x16x32_bf16 v[154:157], v[98:101], v[10:13], 0
	v_exp_f32_e32 v146, v146
	v_exp_f32_e32 v147, v147
	v_mfma_f32_16x16x32_bf16 v[158:161], v[98:101], v[14:17], 0
	v_exp_f32_e32 v148, v148
	v_exp_f32_e32 v149, v149
	s_waitcnt lgkmcnt(2)
	v_mfma_f32_16x16x32_bf16 v[154:157], v[102:105], v[2:5], v[154:157]
	v_exp_f32_e32 v150, v150
	v_exp_f32_e32 v151, v151
	v_mfma_f32_16x16x32_bf16 v[158:161], v[102:105], v[6:9], v[158:161]
	v_exp_f32_e32 v152, v152
	v_exp_f32_e32 v153, v153
	v_cvt_pk_bf16_f32 v114, v138, v139
	v_cvt_pk_bf16_f32 v115, v140, v141
	v_cvt_pk_bf16_f32 v118, v142, v143
	v_cvt_pk_bf16_f32 v119, v144, v145
	ds_read_b128 v[138:141], v170 offset:0
	ds_read_b128 v[142:145], v170 offset:4608
	s_waitcnt lgkmcnt(3)
	v_mfma_f32_16x16x32_bf16 v[162:165], v[106:109], v[10:13], 0
	v_pk_add_f32 v[200:201], v[146:147], v[200:201]
	v_pk_add_f32 v[202:203], v[150:151], v[202:203]
	v_mfma_f32_16x16x32_bf16 v[166:169], v[106:109], v[14:17], 0
	v_pk_add_f32 v[200:201], v[148:149], v[200:201]
	s_waitcnt lgkmcnt(2)
	v_mfma_f32_16x16x32_bf16 v[162:165], v[110:113], v[2:5], v[162:165]
	v_pk_add_f32 v[202:203], v[152:153], v[202:203]
	v_cvt_pk_bf16_f32 v116, v146, v147
	v_cvt_pk_bf16_f32 v117, v148, v149
	v_mfma_f32_16x16x32_bf16 v[166:169], v[110:113], v[6:9], v[166:169]
	v_cvt_pk_bf16_f32 v120, v150, v151
	v_cvt_pk_bf16_f32 v121, v152, v153
	ds_read_b128 v[146:149], v170 offset:9216
	ds_read_b128 v[150:153], v170 offset:13824
	ds_read_b128 v[98:101], v170 offset:18432
	ds_read_b128 v[102:105], v170 offset:23040
	ds_read_b128 v[106:109], v170 offset:27648
	ds_read_b128 v[110:113], v170 offset:32256
	v_exp_f32_e32 v154, v154
	v_exp_f32_e32 v155, v155
	v_exp_f32_e32 v156, v156
	v_exp_f32_e32 v157, v157
	v_exp_f32_e32 v158, v158
	v_exp_f32_e32 v159, v159
	v_exp_f32_e32 v160, v160
	v_exp_f32_e32 v161, v161
	s_waitcnt lgkmcnt(7)
	v_mfma_f32_16x16x32_bf16 v[78:81], v[138:141], v[114:117], v[78:81]
	v_mfma_f32_16x16x32_bf16 v[74:77], v[138:141], v[118:121], v[74:77]
	v_exp_f32_e32 v162, v162
	v_exp_f32_e32 v163, v163
	v_exp_f32_e32 v164, v164
	v_exp_f32_e32 v165, v165
	s_waitcnt lgkmcnt(6)
	v_mfma_f32_16x16x32_bf16 v[70:73], v[142:145], v[114:117], v[70:73]
	v_mfma_f32_16x16x32_bf16 v[62:65], v[142:145], v[118:121], v[62:65]
	v_exp_f32_e32 v166, v166
	v_exp_f32_e32 v167, v167
	v_exp_f32_e32 v168, v168
	v_exp_f32_e32 v169, v169
	s_waitcnt lgkmcnt(5)
	v_mfma_f32_16x16x32_bf16 v[66:69], v[146:149], v[114:117], v[66:69]
	v_mfma_f32_16x16x32_bf16 v[46:49], v[146:149], v[118:121], v[46:49]
	v_pk_add_f32 v[200:201], v[154:155], v[200:201]
	v_pk_add_f32 v[202:203], v[158:159], v[202:203]
	v_pk_add_f32 v[200:201], v[156:157], v[200:201]
	v_pk_add_f32 v[202:203], v[160:161], v[202:203]
	s_waitcnt lgkmcnt(4)
	v_mfma_f32_16x16x32_bf16 v[58:61], v[150:153], v[114:117], v[58:61]
	v_mfma_f32_16x16x32_bf16 v[38:41], v[150:153], v[118:121], v[38:41]
	ds_read_b128 v[138:141], v170 offset:18496
	ds_read_b128 v[142:145], v170 offset:23104
	ds_read_b128 v[146:149], v170 offset:27712
	ds_read_b128 v[150:153], v170 offset:32320
	v_cvt_pk_bf16_f32 v184, v154, v155
	v_cvt_pk_bf16_f32 v185, v156, v157
	v_cvt_pk_bf16_f32 v128, v158, v159
	v_cvt_pk_bf16_f32 v129, v160, v161
	s_waitcnt lgkmcnt(7)
	v_mfma_f32_16x16x32_bf16 v[54:57], v[98:101], v[114:117], v[54:57]
	v_mfma_f32_16x16x32_bf16 v[30:33], v[98:101], v[118:121], v[30:33]
	v_pk_add_f32 v[200:201], v[162:163], v[200:201]
	v_pk_add_f32 v[202:203], v[166:167], v[202:203]
	v_pk_add_f32 v[200:201], v[164:165], v[200:201]
	v_pk_add_f32 v[202:203], v[168:169], v[202:203]
	s_waitcnt lgkmcnt(6)
	v_mfma_f32_16x16x32_bf16 v[50:53], v[102:105], v[114:117], v[50:53]
	v_mfma_f32_16x16x32_bf16 v[26:29], v[102:105], v[118:121], v[26:29]
	v_cvt_pk_bf16_f32 v186, v162, v163
	v_cvt_pk_bf16_f32 v187, v164, v165
	v_cvt_pk_bf16_f32 v130, v166, v167
	v_cvt_pk_bf16_f32 v131, v168, v169
	ds_read_b128 v[154:157], v170 offset:64
	ds_read_b128 v[158:161], v170 offset:4672
	ds_read_b128 v[162:165], v170 offset:9280
	ds_read_b128 v[166:169], v170 offset:13888
	s_waitcnt lgkmcnt(9)
	v_mfma_f32_16x16x32_bf16 v[42:45], v[106:109], v[114:117], v[42:45]
	v_mfma_f32_16x16x32_bf16 v[22:25], v[106:109], v[118:121], v[22:25]
	s_waitcnt lgkmcnt(8)
	v_mfma_f32_16x16x32_bf16 v[34:37], v[110:113], v[114:117], v[34:37]
	v_mfma_f32_16x16x32_bf16 v[18:21], v[110:113], v[118:121], v[18:21]
	ds_read_b128 v[98:101], v136 offset:18432
	ds_read_b128 v[102:105], v136 offset:18496
	ds_read_b128 v[106:109], v136 offset:23040
	ds_read_b128 v[110:113], v136 offset:23104
	s_waitcnt lgkmcnt(7)
	v_mfma_f32_16x16x32_bf16 v[78:81], v[154:157], v[184:187], v[78:81]
	v_mfma_f32_16x16x32_bf16 v[74:77], v[154:157], v[128:131], v[74:77]
	s_waitcnt lgkmcnt(6)
	v_mfma_f32_16x16x32_bf16 v[70:73], v[158:161], v[184:187], v[70:73]
	v_mfma_f32_16x16x32_bf16 v[62:65], v[158:161], v[128:131], v[62:65]
	s_waitcnt vmcnt(3)
	ds_write_b128 v171, v[82:85] offset:0
	s_waitcnt vmcnt(2)
	ds_write_b128 v171, v[86:89] offset:9216
	s_waitcnt vmcnt(1)
	ds_write_b128 v171, v[90:93] offset:18432
	s_waitcnt vmcnt(0)
	ds_write_b128 v171, v[94:97] offset:27648
	s_waitcnt lgkmcnt(9)
	v_mfma_f32_16x16x32_bf16 v[66:69], v[162:165], v[184:187], v[66:69]
	v_mfma_f32_16x16x32_bf16 v[46:49], v[162:165], v[128:131], v[46:49]
	s_waitcnt lgkmcnt(8)
	v_mfma_f32_16x16x32_bf16 v[58:61], v[166:169], v[184:187], v[58:61]
	v_mfma_f32_16x16x32_bf16 v[38:41], v[166:169], v[128:131], v[38:41]
	global_load_dwordx4 v[82:85], v125, s[72:73]
	global_load_dwordx4 v[86:89], v125, s[74:75]
	global_load_dwordx4 v[90:93], v125, s[76:77]
	global_load_dwordx4 v[94:97], v125, s[78:79]
	v_add_u32_e32 v125, s38, v125
	v_mfma_f32_16x16x32_bf16 v[54:57], v[138:141], v[184:187], v[54:57]
	v_mfma_f32_16x16x32_bf16 v[30:33], v[138:141], v[128:131], v[30:33]
	v_mfma_f32_16x16x32_bf16 v[50:53], v[142:145], v[184:187], v[50:53]
	v_mfma_f32_16x16x32_bf16 v[26:29], v[142:145], v[128:131], v[26:29]
	v_mfma_f32_16x16x32_bf16 v[42:45], v[146:149], v[184:187], v[42:45]
	v_mfma_f32_16x16x32_bf16 v[22:25], v[146:149], v[128:131], v[22:25]
	v_mfma_f32_16x16x32_bf16 v[34:37], v[150:153], v[184:187], v[34:37]
	v_mfma_f32_16x16x32_bf16 v[18:21], v[150:153], v[128:131], v[18:21]
	s_waitcnt lgkmcnt(7)
	v_mfma_f32_16x16x32_bf16 v[138:141], v[98:101], v[10:13], 0
	v_mfma_f32_16x16x32_bf16 v[142:145], v[98:101], v[14:17], 0
	s_waitcnt lgkmcnt(6)
	v_mfma_f32_16x16x32_bf16 v[138:141], v[102:105], v[2:5], v[138:141]
	v_mfma_f32_16x16x32_bf16 v[142:145], v[102:105], v[6:9], v[142:145]
	ds_read_b128 v[98:101], v136 offset:27648
	ds_read_b128 v[102:105], v136 offset:27712
	s_waitcnt lgkmcnt(7)
	v_mfma_f32_16x16x32_bf16 v[146:149], v[106:109], v[10:13], 0
	v_mfma_f32_16x16x32_bf16 v[150:153], v[106:109], v[14:17], 0
	s_waitcnt lgkmcnt(6)
	v_mfma_f32_16x16x32_bf16 v[146:149], v[110:113], v[2:5], v[146:149]
	v_mfma_f32_16x16x32_bf16 v[150:153], v[110:113], v[6:9], v[150:153]
	ds_read_b128 v[106:109], v136 offset:32256
	ds_read_b128 v[110:113], v136 offset:32320
	v_exp_f32_e32 v138, v138
	v_exp_f32_e32 v139, v139
	v_exp_f32_e32 v140, v140
	v_exp_f32_e32 v141, v141
	v_exp_f32_e32 v142, v142
	v_exp_f32_e32 v143, v143
	v_exp_f32_e32 v144, v144
	v_exp_f32_e32 v145, v145
	v_pk_add_f32 v[200:201], v[138:139], v[200:201]
	v_pk_add_f32 v[202:203], v[142:143], v[202:203]
	v_pk_add_f32 v[200:201], v[140:141], v[200:201]
	v_pk_add_f32 v[202:203], v[144:145], v[202:203]
	s_waitcnt lgkmcnt(3)
	v_mfma_f32_16x16x32_bf16 v[154:157], v[98:101], v[10:13], 0
	v_exp_f32_e32 v146, v146
	v_exp_f32_e32 v147, v147
	v_mfma_f32_16x16x32_bf16 v[158:161], v[98:101], v[14:17], 0
	v_exp_f32_e32 v148, v148
	v_exp_f32_e32 v149, v149
	s_waitcnt lgkmcnt(2)
	v_mfma_f32_16x16x32_bf16 v[154:157], v[102:105], v[2:5], v[154:157]
	v_exp_f32_e32 v150, v150
	v_exp_f32_e32 v151, v151
	v_mfma_f32_16x16x32_bf16 v[158:161], v[102:105], v[6:9], v[158:161]
	v_exp_f32_e32 v152, v152
	v_exp_f32_e32 v153, v153
	v_cvt_pk_bf16_f32 v114, v138, v139
	v_cvt_pk_bf16_f32 v115, v140, v141
	v_cvt_pk_bf16_f32 v118, v142, v143
	v_cvt_pk_bf16_f32 v119, v144, v145
	ds_read_b128 v[138:141], v170 offset:128
	ds_read_b128 v[142:145], v170 offset:4736
	s_waitcnt lgkmcnt(3)
	v_mfma_f32_16x16x32_bf16 v[162:165], v[106:109], v[10:13], 0
	v_pk_add_f32 v[200:201], v[146:147], v[200:201]
	v_pk_add_f32 v[202:203], v[150:151], v[202:203]
	v_mfma_f32_16x16x32_bf16 v[166:169], v[106:109], v[14:17], 0
	v_pk_add_f32 v[200:201], v[148:149], v[200:201]
	s_waitcnt lgkmcnt(2)
	v_mfma_f32_16x16x32_bf16 v[162:165], v[110:113], v[2:5], v[162:165]
	v_pk_add_f32 v[202:203], v[152:153], v[202:203]
	v_cvt_pk_bf16_f32 v116, v146, v147
	v_cvt_pk_bf16_f32 v117, v148, v149
	v_mfma_f32_16x16x32_bf16 v[166:169], v[110:113], v[6:9], v[166:169]
	v_cvt_pk_bf16_f32 v120, v150, v151
	v_cvt_pk_bf16_f32 v121, v152, v153
	ds_read_b128 v[146:149], v170 offset:9344
	ds_read_b128 v[150:153], v170 offset:13952
	ds_read_b128 v[98:101], v170 offset:18560
	ds_read_b128 v[102:105], v170 offset:23168
	ds_read_b128 v[106:109], v170 offset:27776
	ds_read_b128 v[110:113], v170 offset:32384
	v_exp_f32_e32 v154, v154
	v_exp_f32_e32 v155, v155
	v_exp_f32_e32 v156, v156
	v_exp_f32_e32 v157, v157
	v_exp_f32_e32 v158, v158
	v_exp_f32_e32 v159, v159
	v_exp_f32_e32 v160, v160
	v_exp_f32_e32 v161, v161
	s_waitcnt lgkmcnt(7)
	v_mfma_f32_16x16x32_bf16 v[78:81], v[138:141], v[114:117], v[78:81]
	v_mfma_f32_16x16x32_bf16 v[74:77], v[138:141], v[118:121], v[74:77]
	v_exp_f32_e32 v162, v162
	v_exp_f32_e32 v163, v163
	v_exp_f32_e32 v164, v164
	v_exp_f32_e32 v165, v165
	s_waitcnt lgkmcnt(6)
	v_mfma_f32_16x16x32_bf16 v[70:73], v[142:145], v[114:117], v[70:73]
	v_mfma_f32_16x16x32_bf16 v[62:65], v[142:145], v[118:121], v[62:65]
	v_exp_f32_e32 v166, v166
	v_exp_f32_e32 v167, v167
	v_exp_f32_e32 v168, v168
	v_exp_f32_e32 v169, v169
	s_waitcnt lgkmcnt(5)
	v_mfma_f32_16x16x32_bf16 v[66:69], v[146:149], v[114:117], v[66:69]
	v_mfma_f32_16x16x32_bf16 v[46:49], v[146:149], v[118:121], v[46:49]
	v_pk_add_f32 v[200:201], v[154:155], v[200:201]
	v_pk_add_f32 v[202:203], v[158:159], v[202:203]
	v_pk_add_f32 v[200:201], v[156:157], v[200:201]
	v_pk_add_f32 v[202:203], v[160:161], v[202:203]
	s_waitcnt lgkmcnt(4)
	v_mfma_f32_16x16x32_bf16 v[58:61], v[150:153], v[114:117], v[58:61]
	v_mfma_f32_16x16x32_bf16 v[38:41], v[150:153], v[118:121], v[38:41]
	ds_read_b128 v[138:141], v170 offset:18624
	ds_read_b128 v[142:145], v170 offset:23232
	ds_read_b128 v[146:149], v170 offset:27840
	ds_read_b128 v[150:153], v170 offset:32448
	v_cvt_pk_bf16_f32 v184, v154, v155
	v_cvt_pk_bf16_f32 v185, v156, v157
	v_cvt_pk_bf16_f32 v128, v158, v159
	v_cvt_pk_bf16_f32 v129, v160, v161
	s_waitcnt lgkmcnt(7)
	v_mfma_f32_16x16x32_bf16 v[54:57], v[98:101], v[114:117], v[54:57]
	v_mfma_f32_16x16x32_bf16 v[30:33], v[98:101], v[118:121], v[30:33]
	v_pk_add_f32 v[200:201], v[162:163], v[200:201]
	v_pk_add_f32 v[202:203], v[166:167], v[202:203]
	v_pk_add_f32 v[200:201], v[164:165], v[200:201]
	v_pk_add_f32 v[202:203], v[168:169], v[202:203]
	s_waitcnt lgkmcnt(6)
	v_mfma_f32_16x16x32_bf16 v[50:53], v[102:105], v[114:117], v[50:53]
	v_mfma_f32_16x16x32_bf16 v[26:29], v[102:105], v[118:121], v[26:29]
	v_cvt_pk_bf16_f32 v186, v162, v163
	v_cvt_pk_bf16_f32 v187, v164, v165
	v_cvt_pk_bf16_f32 v130, v166, v167
	v_cvt_pk_bf16_f32 v131, v168, v169
	ds_read_b128 v[154:157], v170 offset:192
	ds_read_b128 v[158:161], v170 offset:4800
	ds_read_b128 v[162:165], v170 offset:9408
	ds_read_b128 v[166:169], v170 offset:14016
	s_waitcnt lgkmcnt(9)
	v_mfma_f32_16x16x32_bf16 v[42:45], v[106:109], v[114:117], v[42:45]
	v_mfma_f32_16x16x32_bf16 v[22:25], v[106:109], v[118:121], v[22:25]
	s_waitcnt lgkmcnt(8)
	v_mfma_f32_16x16x32_bf16 v[34:37], v[110:113], v[114:117], v[34:37]
	v_mfma_f32_16x16x32_bf16 v[18:21], v[110:113], v[118:121], v[18:21]
	s_waitcnt lgkmcnt(3)
	v_mfma_f32_16x16x32_bf16 v[78:81], v[154:157], v[184:187], v[78:81]
	v_mfma_f32_16x16x32_bf16 v[74:77], v[154:157], v[128:131], v[74:77]
	s_waitcnt lgkmcnt(2)
	v_mfma_f32_16x16x32_bf16 v[70:73], v[158:161], v[184:187], v[70:73]
	v_mfma_f32_16x16x32_bf16 v[62:65], v[158:161], v[128:131], v[62:65]
	s_waitcnt lgkmcnt(1)
	v_mfma_f32_16x16x32_bf16 v[66:69], v[162:165], v[184:187], v[66:69]
	v_mfma_f32_16x16x32_bf16 v[46:49], v[162:165], v[128:131], v[46:49]
	s_waitcnt lgkmcnt(0)
	v_mfma_f32_16x16x32_bf16 v[58:61], v[166:169], v[184:187], v[58:61]
	v_mfma_f32_16x16x32_bf16 v[38:41], v[166:169], v[128:131], v[38:41]
	s_waitcnt vmcnt(3)
	ds_write_b128 v173, v[82:85] offset:0
	s_waitcnt vmcnt(2)
	ds_write_b128 v173, v[86:89] offset:9216
	s_waitcnt vmcnt(1)
	ds_write_b128 v173, v[90:93] offset:18432
	s_waitcnt vmcnt(0)
	ds_write_b128 v173, v[94:97] offset:27648
	v_mfma_f32_16x16x32_bf16 v[54:57], v[138:141], v[184:187], v[54:57]
	v_mfma_f32_16x16x32_bf16 v[30:33], v[138:141], v[128:131], v[30:33]
	v_mfma_f32_16x16x32_bf16 v[50:53], v[142:145], v[184:187], v[50:53]
	v_mfma_f32_16x16x32_bf16 v[26:29], v[142:145], v[128:131], v[26:29]
	v_mfma_f32_16x16x32_bf16 v[42:45], v[146:149], v[184:187], v[42:45]
	v_mfma_f32_16x16x32_bf16 v[22:25], v[146:149], v[128:131], v[22:25]
	v_mfma_f32_16x16x32_bf16 v[34:37], v[150:153], v[184:187], v[34:37]
	v_mfma_f32_16x16x32_bf16 v[18:21], v[150:153], v[128:131], v[18:21]
	s_waitcnt lgkmcnt(0)
	s_barrier
	s_add_i32 s15, s15, 1
	s_cmp_eq_u32 s15, 33
	s_cbranch_scc0 .Lattn_nf_loop
	v_add_f32_e32 v123, v200, v201
	v_add_f32_e32 v122, v202, v203
	v_readlane_b32 s64, v175, 0
	v_readlane_b32 s65, v175, 1
	v_readlane_b32 s66, v175, 2
	v_readlane_b32 s67, v175, 3
	v_readlane_b32 s68, v175, 4
	v_readlane_b32 s69, v175, 5
	v_readlane_b32 s70, v175, 6
	v_readlane_b32 s71, v175, 7
	v_readlane_b32 s72, v175, 8
	v_readlane_b32 s73, v175, 9
	v_readlane_b32 s74, v175, 10
	v_readlane_b32 s75, v175, 11
	v_readlane_b32 s76, v175, 12
	v_readlane_b32 s77, v175, 13
	v_readlane_b32 s78, v175, 14
	v_readlane_b32 s79, v175, 15
	s_nop 4
	v_add_u32_e32 v216, 0x9000, v137
	v_add_u32_e32 v217, 0x9000, v183
	ds_read_b128 v[82:85], v216 offset:0
	ds_read_b128 v[90:93], v216 offset:64
	v_add_f32_e32 v186, v132, v134
	v_add_f32_e32 v184, v133, v135
	ds_bpermute_b32 v187, v172, v186
	ds_bpermute_b32 v185, v172, v184
	s_mov_b32 s10, 0x3fb8aa3b
	s_mov_b32 s11, 0xc2ce8ed0
	s_mov_b32 s6, 0x42b17218
	s_waitcnt lgkmcnt(3)
	v_mfma_f32_16x16x32_bf16 v[86:89], v[82:85], v[10:13], 0
	v_cmp_eq_u32_e64 s[40:41], 0, v179
	s_lshl_b32 s30, s14, 1
	v_lshlrev_b32_e32 v196, 3, v178
	v_mov_b32_e32 v197, 0
	v_lshlrev_b32_e32 v198, 4, v179
	v_or3_b32 v198, v198, v177, v180
	v_ashrrev_i32_e32 v199, 31, v198
	v_lshlrev_b64 v[198:199], 11, v[198:199]
	s_mov_b64 s[100:101], 0x18a10000
	v_lshl_add_u64 v[198:199], s[42:43], 0, v[198:199]
	v_lshl_add_u64 v[198:199], v[198:199], 0, s[30:31]
	v_lshl_add_u64 v[198:199], v[198:199], 0, v[196:197]
	v_lshl_add_u64 v[198:199], v[198:199], 0, s[100:101]
	global_load_dwordx2 v[146:147], v[198:199], off
	global_load_dwordx2 v[148:149], v[198:199], off offset:32
	global_load_dwordx2 v[150:151], v[198:199], off offset:64
	global_load_dwordx2 v[152:153], v[198:199], off offset:96
	global_load_dwordx2 v[188:189], v[198:199], off offset:128
	global_load_dwordx2 v[190:191], v[198:199], off offset:160
	global_load_dwordx2 v[192:193], v[198:199], off offset:192
	global_load_dwordx2 v[194:195], v[198:199], off offset:224
	s_mov_b64 s[100:101], exec
	s_and_b64 exec, exec, s[4:5]
	s_cbranch_execz .Lpop_skip
	v_readlane_b32 s14, v255, 22
	v_readlane_b32 s15, v255, 23
	v_mov_b32_e32 v224, 1
	s_nop 4
	global_atomic_add v224, v0, v224, s[14:15] sc0
